# HGRN cross-chunk scan hand-written: 64 chunk steps fully unrolled per lane with the U/D loads of 16 steps in flight behind counted vmcnt (hipcc waited vmcnt(0) after every step); same arithmetic and o
# speedup vs baseline: 1.0679x; 1.0174x over previous
; __device__ __forceinline__ unsigned cvt_pk_bf16(float lo, float hi) { unsigned r; asm volatile("v_cvt_pk_bf16_f32 %0, %1, %2" : "=v"(r) : "v"(lo), "v"(hi)); return r; }
; __device__ __forceinline__ float bflo(unsigned w) { return __uint_as_float(w << 16); }
; __device__ __forceinline__ float bfhi(unsigned w) { return __uint_as_float(w & 0xffff0000u); }
; __device__ void hgrn_scan(const float* ust, const float* ddec, bf16_t* sst, const int WID) {
;     for (int e4 = blockIdx.x * 512 + TID_X; e4 < 32 * 4096; e4 += gridDim.x * 512) {
;         const int bh = e4 >> 12, off = (e4 & 4095) * 4, d = off & 127;
;         f32x4 S = (f32x4){0.f, 0.f, 0.f, 0.f};
;         const bf16_t* up = (const bf16_t*)ust + (size_t)bh * 64 * 16384 + off; const float* dp = ddec + (size_t)bh * 64 * 128 + d; bf16_t* sp = sst + (size_t)bh * 64 * 16384 + off;
; #pragma unroll 16
;         for (int c = 0; c < 64; ++c) {
;             const u32x2 uw = *(const u32x2*)(up + (size_t)c * 16384); const f32x4 U = (f32x4){bflo(uw.x), bfhi(uw.x), bflo(uw.y), bfhi(uw.y)}; const f32x4 Dv = *(const f32x4*)(dp + c * 128);
;             u32x2 w; w.x = cvt_pk_bf16(S[0], S[1]); w.y = cvt_pk_bf16(S[2], S[3]); *(u32x2*)(sp + (size_t)c * 16384) = w;
;             S = Dv * S + U;
;         }
;     }
; }
.LBB0_216:
	v_ashrrev_i32_e32 v2, 12, v1
	v_lshlrev_b32_e32 v236, 21, v2
	v_lshlrev_b32_e32 v240, 1, v18
	s_movk_i32 s28, 0x7ff8
	v_lshlrev_b32_e32 v237, 15, v2
	v_and_or_b32 v236, v240, s28, v236
	v_lshlrev_b32_e32 v240, 2, v18
	s_movk_i32 s28, 0x1f0
	s_mov_b64 s[98:99], s[90:91]
	s_add_u32 s100, s4, 0xffffe200
	s_addc_u32 s101, s5, -1
	s_add_u32 s12, s94, 0x18f00000
	s_addc_u32 s13, s95, 0
	v_and_or_b32 v237, v240, s28, v237
	v_mov_b32_e32 v222, 0
	v_mov_b32_e32 v223, 0
	v_mov_b32_e32 v224, 0
	v_mov_b32_e32 v225, 0
	global_load_dwordx2 v[186:187], v236, s[98:99]
	global_load_dwordx4 v[4:7], v237, s[100:101]
	s_add_u32 s98, s98, 0x8000
	s_addc_u32 s99, s99, 0
	global_load_dwordx2 v[188:189], v236, s[98:99]
	global_load_dwordx4 v[8:11], v237, s[100:101] offset:512
	s_add_u32 s98, s98, 0x8000
	s_addc_u32 s99, s99, 0
	global_load_dwordx2 v[190:191], v236, s[98:99]
	global_load_dwordx4 v[12:15], v237, s[100:101] offset:1024
	s_add_u32 s98, s98, 0x8000
	s_addc_u32 s99, s99, 0
	global_load_dwordx2 v[192:193], v236, s[98:99]
	global_load_dwordx4 v[16:19], v237, s[100:101] offset:1536
	s_add_u32 s98, s98, 0x8000
	s_addc_u32 s99, s99, 0
	global_load_dwordx2 v[194:195], v236, s[98:99]
	global_load_dwordx4 v[20:23], v237, s[100:101] offset:2048
	s_add_u32 s98, s98, 0x8000
	s_addc_u32 s99, s99, 0
	global_load_dwordx2 v[196:197], v236, s[98:99]
	global_load_dwordx4 v[24:27], v237, s[100:101] offset:2560
	s_add_u32 s98, s98, 0x8000
	s_addc_u32 s99, s99, 0
	global_load_dwordx2 v[198:199], v236, s[98:99]
	global_load_dwordx4 v[28:31], v237, s[100:101] offset:3072
	s_add_u32 s98, s98, 0x8000
	s_addc_u32 s99, s99, 0
	global_load_dwordx2 v[200:201], v236, s[98:99]
	global_load_dwordx4 v[32:35], v237, s[100:101] offset:3584
	s_add_u32 s98, s98, 0x8000
	s_addc_u32 s99, s99, 0
	s_add_u32 s100, s100, 0x1000
	s_addc_u32 s101, s101, 0
	global_load_dwordx2 v[202:203], v236, s[98:99]
	global_load_dwordx4 v[116:119], v237, s[100:101]
	s_add_u32 s98, s98, 0x8000
	s_addc_u32 s99, s99, 0
	global_load_dwordx2 v[204:205], v236, s[98:99]
	global_load_dwordx4 v[120:123], v237, s[100:101] offset:512
	s_add_u32 s98, s98, 0x8000
	s_addc_u32 s99, s99, 0
	global_load_dwordx2 v[206:207], v236, s[98:99]
	global_load_dwordx4 v[124:127], v237, s[100:101] offset:1024
	s_add_u32 s98, s98, 0x8000
	s_addc_u32 s99, s99, 0
	global_load_dwordx2 v[214:215], v236, s[98:99]
	global_load_dwordx4 v[128:131], v237, s[100:101] offset:1536
	s_add_u32 s98, s98, 0x8000
	s_addc_u32 s99, s99, 0
	global_load_dwordx2 v[216:217], v236, s[98:99]
	global_load_dwordx4 v[164:167], v237, s[100:101] offset:2048
	s_add_u32 s98, s98, 0x8000
	s_addc_u32 s99, s99, 0
	global_load_dwordx2 v[218:219], v236, s[98:99]
	global_load_dwordx4 v[168:171], v237, s[100:101] offset:2560
	s_add_u32 s98, s98, 0x8000
	s_addc_u32 s99, s99, 0
	global_load_dwordx2 v[220:221], v236, s[98:99]
	global_load_dwordx4 v[172:175], v237, s[100:101] offset:3072
	s_add_u32 s98, s98, 0x8000
	s_addc_u32 s99, s99, 0
	global_load_dwordx2 v[44:45], v236, s[98:99]
	global_load_dwordx4 v[176:179], v237, s[100:101] offset:3584
	s_add_u32 s98, s98, 0x8000
	s_addc_u32 s99, s99, 0
	s_add_u32 s100, s100, 0x1000
	s_addc_u32 s101, s101, 0
	s_waitcnt vmcnt(30)
	v_cvt_pk_bf16_f32 v234, v222, v223
	v_cvt_pk_bf16_f32 v235, v224, v225
	v_lshlrev_b32_e32 v226, 16, v186
	v_and_b32_e32 v227, 0xffff0000, v186
	v_lshlrev_b32_e32 v228, 16, v187
	v_and_b32_e32 v229, 0xffff0000, v187
	global_store_dwordx2 v236, v[234:235], s[12:13]
	v_pk_fma_f32 v[222:223], v[222:223], v[4:5], v[226:227]
	v_pk_fma_f32 v[224:225], v[224:225], v[6:7], v[228:229]
	s_add_u32 s12, s12, 0x8000
	s_addc_u32 s13, s13, 0
	global_load_dwordx2 v[186:187], v236, s[98:99]
	global_load_dwordx4 v[4:7], v237, s[100:101]
	s_add_u32 s98, s98, 0x8000
	s_addc_u32 s99, s99, 0
	s_waitcnt vmcnt(31)
	v_cvt_pk_bf16_f32 v238, v222, v223
	v_cvt_pk_bf16_f32 v239, v224, v225
	v_lshlrev_b32_e32 v226, 16, v188
	v_and_b32_e32 v227, 0xffff0000, v188
	v_lshlrev_b32_e32 v228, 16, v189
	v_and_b32_e32 v229, 0xffff0000, v189
	global_store_dwordx2 v236, v[238:239], s[12:13]
	v_pk_fma_f32 v[222:223], v[222:223], v[8:9], v[226:227]
	v_pk_fma_f32 v[224:225], v[224:225], v[10:11], v[228:229]
	s_add_u32 s12, s12, 0x8000
	s_addc_u32 s13, s13, 0
	global_load_dwordx2 v[188:189], v236, s[98:99]
	global_load_dwordx4 v[8:11], v237, s[100:101] offset:512
	s_add_u32 s98, s98, 0x8000
	s_addc_u32 s99, s99, 0
	s_waitcnt vmcnt(32)
	v_cvt_pk_bf16_f32 v234, v222, v223
	v_cvt_pk_bf16_f32 v235, v224, v225
	v_lshlrev_b32_e32 v226, 16, v190
	v_and_b32_e32 v227, 0xffff0000, v190
	v_lshlrev_b32_e32 v228, 16, v191
	v_and_b32_e32 v229, 0xffff0000, v191
	global_store_dwordx2 v236, v[234:235], s[12:13]
	v_pk_fma_f32 v[222:223], v[222:223], v[12:13], v[226:227]
	v_pk_fma_f32 v[224:225], v[224:225], v[14:15], v[228:229]
	s_add_u32 s12, s12, 0x8000
	s_addc_u32 s13, s13, 0
	global_load_dwordx2 v[190:191], v236, s[98:99]
	global_load_dwordx4 v[12:15], v237, s[100:101] offset:1024
	s_add_u32 s98, s98, 0x8000
	s_addc_u32 s99, s99, 0
	s_waitcnt vmcnt(33)
	v_cvt_pk_bf16_f32 v238, v222, v223
	v_cvt_pk_bf16_f32 v239, v224, v225
	v_lshlrev_b32_e32 v226, 16, v192
	v_and_b32_e32 v227, 0xffff0000, v192
	v_lshlrev_b32_e32 v228, 16, v193
	v_and_b32_e32 v229, 0xffff0000, v193
	global_store_dwordx2 v236, v[238:239], s[12:13]
	v_pk_fma_f32 v[222:223], v[222:223], v[16:17], v[226:227]
	v_pk_fma_f32 v[224:225], v[224:225], v[18:19], v[228:229]
	s_add_u32 s12, s12, 0x8000
	s_addc_u32 s13, s13, 0
	global_load_dwordx2 v[192:193], v236, s[98:99]
	global_load_dwordx4 v[16:19], v237, s[100:101] offset:1536
	s_add_u32 s98, s98, 0x8000
	s_addc_u32 s99, s99, 0
	s_waitcnt vmcnt(34)
; __device__ __forceinline__ unsigned cvt_pk_bf16(float lo, float hi) { unsigned r; asm volatile("v_cvt_pk_bf16_f32 %0, %1, %2" : "=v"(r) : "v"(lo), "v"(hi)); return r; }
; __device__ __forceinline__ float bflo(unsigned w) { return __uint_as_float(w << 16); }
; __device__ __forceinline__ float bfhi(unsigned w) { return __uint_as_float(w & 0xffff0000u); }
; __device__ void hgrn_scan(const float* ust, const float* ddec, bf16_t* sst, const int WID) {
;     ...
;         for (int c = 0; c < 64; ++c) {
;             const u32x2 uw = *(const u32x2*)(up + (size_t)c * 16384); const f32x4 U = (f32x4){bflo(uw.x), bfhi(uw.x), bflo(uw.y), bfhi(uw.y)}; const f32x4 Dv = *(const f32x4*)(dp + c * 128);
;             u32x2 w; w.x = cvt_pk_bf16(S[0], S[1]); w.y = cvt_pk_bf16(S[2], S[3]); *(u32x2*)(sp + (size_t)c * 16384) = w;
;             S = Dv * S + U;
;         }
	v_cvt_pk_bf16_f32 v234, v222, v223
	v_cvt_pk_bf16_f32 v235, v224, v225
	v_lshlrev_b32_e32 v226, 16, v194
	v_and_b32_e32 v227, 0xffff0000, v194
	v_lshlrev_b32_e32 v228, 16, v195
	v_and_b32_e32 v229, 0xffff0000, v195
	global_store_dwordx2 v236, v[234:235], s[12:13]
	v_pk_fma_f32 v[222:223], v[222:223], v[20:21], v[226:227]
	v_pk_fma_f32 v[224:225], v[224:225], v[22:23], v[228:229]
	s_add_u32 s12, s12, 0x8000
	s_addc_u32 s13, s13, 0
	global_load_dwordx2 v[194:195], v236, s[98:99]
	global_load_dwordx4 v[20:23], v237, s[100:101] offset:2048
	s_add_u32 s98, s98, 0x8000
	s_addc_u32 s99, s99, 0
	s_waitcnt vmcnt(35)
	v_cvt_pk_bf16_f32 v238, v222, v223
	v_cvt_pk_bf16_f32 v239, v224, v225
	v_lshlrev_b32_e32 v226, 16, v196
	v_and_b32_e32 v227, 0xffff0000, v196
	v_lshlrev_b32_e32 v228, 16, v197
	v_and_b32_e32 v229, 0xffff0000, v197
	global_store_dwordx2 v236, v[238:239], s[12:13]
	v_pk_fma_f32 v[222:223], v[222:223], v[24:25], v[226:227]
	v_pk_fma_f32 v[224:225], v[224:225], v[26:27], v[228:229]
	s_add_u32 s12, s12, 0x8000
	s_addc_u32 s13, s13, 0
	global_load_dwordx2 v[196:197], v236, s[98:99]
	global_load_dwordx4 v[24:27], v237, s[100:101] offset:2560
	s_add_u32 s98, s98, 0x8000
	s_addc_u32 s99, s99, 0
	s_waitcnt vmcnt(36)
	v_cvt_pk_bf16_f32 v234, v222, v223
	v_cvt_pk_bf16_f32 v235, v224, v225
	v_lshlrev_b32_e32 v226, 16, v198
	v_and_b32_e32 v227, 0xffff0000, v198
	v_lshlrev_b32_e32 v228, 16, v199
	v_and_b32_e32 v229, 0xffff0000, v199
	global_store_dwordx2 v236, v[234:235], s[12:13]
	v_pk_fma_f32 v[222:223], v[222:223], v[28:29], v[226:227]
	v_pk_fma_f32 v[224:225], v[224:225], v[30:31], v[228:229]
	s_add_u32 s12, s12, 0x8000
	s_addc_u32 s13, s13, 0
	global_load_dwordx2 v[198:199], v236, s[98:99]
	global_load_dwordx4 v[28:31], v237, s[100:101] offset:3072
	s_add_u32 s98, s98, 0x8000
	s_addc_u32 s99, s99, 0
	s_waitcnt vmcnt(37)
	v_cvt_pk_bf16_f32 v238, v222, v223
	v_cvt_pk_bf16_f32 v239, v224, v225
	v_lshlrev_b32_e32 v226, 16, v200
	v_and_b32_e32 v227, 0xffff0000, v200
	v_lshlrev_b32_e32 v228, 16, v201
	v_and_b32_e32 v229, 0xffff0000, v201
	global_store_dwordx2 v236, v[238:239], s[12:13]
	v_pk_fma_f32 v[222:223], v[222:223], v[32:33], v[226:227]
	v_pk_fma_f32 v[224:225], v[224:225], v[34:35], v[228:229]
	s_add_u32 s12, s12, 0x8000
	s_addc_u32 s13, s13, 0
	global_load_dwordx2 v[200:201], v236, s[98:99]
	global_load_dwordx4 v[32:35], v237, s[100:101] offset:3584
	s_add_u32 s98, s98, 0x8000
	s_addc_u32 s99, s99, 0
	s_add_u32 s100, s100, 0x1000
	s_addc_u32 s101, s101, 0
	s_waitcnt vmcnt(38)
	v_cvt_pk_bf16_f32 v234, v222, v223
	v_cvt_pk_bf16_f32 v235, v224, v225
	v_lshlrev_b32_e32 v226, 16, v202
	v_and_b32_e32 v227, 0xffff0000, v202
	v_lshlrev_b32_e32 v228, 16, v203
	v_and_b32_e32 v229, 0xffff0000, v203
	global_store_dwordx2 v236, v[234:235], s[12:13]
	v_pk_fma_f32 v[222:223], v[222:223], v[116:117], v[226:227]
	v_pk_fma_f32 v[224:225], v[224:225], v[118:119], v[228:229]
	s_add_u32 s12, s12, 0x8000
	s_addc_u32 s13, s13, 0
	global_load_dwordx2 v[202:203], v236, s[98:99]
	global_load_dwordx4 v[116:119], v237, s[100:101]
	s_add_u32 s98, s98, 0x8000
	s_addc_u32 s99, s99, 0
	s_waitcnt vmcnt(39)
	v_cvt_pk_bf16_f32 v238, v222, v223
	v_cvt_pk_bf16_f32 v239, v224, v225
	v_lshlrev_b32_e32 v226, 16, v204
	v_and_b32_e32 v227, 0xffff0000, v204
	v_lshlrev_b32_e32 v228, 16, v205
	v_and_b32_e32 v229, 0xffff0000, v205
	global_store_dwordx2 v236, v[238:239], s[12:13]
	v_pk_fma_f32 v[222:223], v[222:223], v[120:121], v[226:227]
	v_pk_fma_f32 v[224:225], v[224:225], v[122:123], v[228:229]
	s_add_u32 s12, s12, 0x8000
	s_addc_u32 s13, s13, 0
	global_load_dwordx2 v[204:205], v236, s[98:99]
	global_load_dwordx4 v[120:123], v237, s[100:101] offset:512
	s_add_u32 s98, s98, 0x8000
	s_addc_u32 s99, s99, 0
	s_waitcnt vmcnt(40)
	v_cvt_pk_bf16_f32 v234, v222, v223
	v_cvt_pk_bf16_f32 v235, v224, v225
	v_lshlrev_b32_e32 v226, 16, v206
	v_and_b32_e32 v227, 0xffff0000, v206
	v_lshlrev_b32_e32 v228, 16, v207
	v_and_b32_e32 v229, 0xffff0000, v207
	global_store_dwordx2 v236, v[234:235], s[12:13]
	v_pk_fma_f32 v[222:223], v[222:223], v[124:125], v[226:227]
	v_pk_fma_f32 v[224:225], v[224:225], v[126:127], v[228:229]
	s_add_u32 s12, s12, 0x8000
	s_addc_u32 s13, s13, 0
	global_load_dwordx2 v[206:207], v236, s[98:99]
	global_load_dwordx4 v[124:127], v237, s[100:101] offset:1024
	s_add_u32 s98, s98, 0x8000
	s_addc_u32 s99, s99, 0
	s_waitcnt vmcnt(41)
	v_cvt_pk_bf16_f32 v238, v222, v223
	v_cvt_pk_bf16_f32 v239, v224, v225
	v_lshlrev_b32_e32 v226, 16, v214
	v_and_b32_e32 v227, 0xffff0000, v214
	v_lshlrev_b32_e32 v228, 16, v215
	v_and_b32_e32 v229, 0xffff0000, v215
	global_store_dwordx2 v236, v[238:239], s[12:13]
	v_pk_fma_f32 v[222:223], v[222:223], v[128:129], v[226:227]
	v_pk_fma_f32 v[224:225], v[224:225], v[130:131], v[228:229]
	s_add_u32 s12, s12, 0x8000
	s_addc_u32 s13, s13, 0
	global_load_dwordx2 v[214:215], v236, s[98:99]
	global_load_dwordx4 v[128:131], v237, s[100:101] offset:1536
	s_add_u32 s98, s98, 0x8000
	s_addc_u32 s99, s99, 0
	s_waitcnt vmcnt(42)
	v_cvt_pk_bf16_f32 v234, v222, v223
	v_cvt_pk_bf16_f32 v235, v224, v225
	v_lshlrev_b32_e32 v226, 16, v216
	v_and_b32_e32 v227, 0xffff0000, v216
	v_lshlrev_b32_e32 v228, 16, v217
	v_and_b32_e32 v229, 0xffff0000, v217
	global_store_dwordx2 v236, v[234:235], s[12:13]
	v_pk_fma_f32 v[222:223], v[222:223], v[164:165], v[226:227]
	v_pk_fma_f32 v[224:225], v[224:225], v[166:167], v[228:229]
	s_add_u32 s12, s12, 0x8000
	s_addc_u32 s13, s13, 0
	global_load_dwordx2 v[216:217], v236, s[98:99]
	global_load_dwordx4 v[164:167], v237, s[100:101] offset:2048
	s_add_u32 s98, s98, 0x8000
	s_addc_u32 s99, s99, 0
	s_waitcnt vmcnt(43)
; __device__ __forceinline__ unsigned cvt_pk_bf16(float lo, float hi) { unsigned r; asm volatile("v_cvt_pk_bf16_f32 %0, %1, %2" : "=v"(r) : "v"(lo), "v"(hi)); return r; }
; __device__ __forceinline__ float bflo(unsigned w) { return __uint_as_float(w << 16); }
; __device__ __forceinline__ float bfhi(unsigned w) { return __uint_as_float(w & 0xffff0000u); }
; __device__ void hgrn_scan(const float* ust, const float* ddec, bf16_t* sst, const int WID) {
;     ...
;         for (int c = 0; c < 64; ++c) {
;             const u32x2 uw = *(const u32x2*)(up + (size_t)c * 16384); const f32x4 U = (f32x4){bflo(uw.x), bfhi(uw.x), bflo(uw.y), bfhi(uw.y)}; const f32x4 Dv = *(const f32x4*)(dp + c * 128);
;             u32x2 w; w.x = cvt_pk_bf16(S[0], S[1]); w.y = cvt_pk_bf16(S[2], S[3]); *(u32x2*)(sp + (size_t)c * 16384) = w;
;             S = Dv * S + U;
;         }
	v_cvt_pk_bf16_f32 v238, v222, v223
	v_cvt_pk_bf16_f32 v239, v224, v225
	v_lshlrev_b32_e32 v226, 16, v218
	v_and_b32_e32 v227, 0xffff0000, v218
	v_lshlrev_b32_e32 v228, 16, v219
	v_and_b32_e32 v229, 0xffff0000, v219
	global_store_dwordx2 v236, v[238:239], s[12:13]
	v_pk_fma_f32 v[222:223], v[222:223], v[168:169], v[226:227]
	v_pk_fma_f32 v[224:225], v[224:225], v[170:171], v[228:229]
	s_add_u32 s12, s12, 0x8000
	s_addc_u32 s13, s13, 0
	global_load_dwordx2 v[218:219], v236, s[98:99]
	global_load_dwordx4 v[168:171], v237, s[100:101] offset:2560
	s_add_u32 s98, s98, 0x8000
	s_addc_u32 s99, s99, 0
	s_waitcnt vmcnt(44)
	v_cvt_pk_bf16_f32 v234, v222, v223
	v_cvt_pk_bf16_f32 v235, v224, v225
	v_lshlrev_b32_e32 v226, 16, v220
	v_and_b32_e32 v227, 0xffff0000, v220
	v_lshlrev_b32_e32 v228, 16, v221
	v_and_b32_e32 v229, 0xffff0000, v221
	global_store_dwordx2 v236, v[234:235], s[12:13]
	v_pk_fma_f32 v[222:223], v[222:223], v[172:173], v[226:227]
	v_pk_fma_f32 v[224:225], v[224:225], v[174:175], v[228:229]
	s_add_u32 s12, s12, 0x8000
	s_addc_u32 s13, s13, 0
	global_load_dwordx2 v[220:221], v236, s[98:99]
	global_load_dwordx4 v[172:175], v237, s[100:101] offset:3072
	s_add_u32 s98, s98, 0x8000
	s_addc_u32 s99, s99, 0
	s_waitcnt vmcnt(45)
	v_cvt_pk_bf16_f32 v238, v222, v223
	v_cvt_pk_bf16_f32 v239, v224, v225
	v_lshlrev_b32_e32 v226, 16, v44
	v_and_b32_e32 v227, 0xffff0000, v44
	v_lshlrev_b32_e32 v228, 16, v45
	v_and_b32_e32 v229, 0xffff0000, v45
	global_store_dwordx2 v236, v[238:239], s[12:13]
	v_pk_fma_f32 v[222:223], v[222:223], v[176:177], v[226:227]
	v_pk_fma_f32 v[224:225], v[224:225], v[178:179], v[228:229]
	s_add_u32 s12, s12, 0x8000
	s_addc_u32 s13, s13, 0
	global_load_dwordx2 v[44:45], v236, s[98:99]
	global_load_dwordx4 v[176:179], v237, s[100:101] offset:3584
	s_add_u32 s98, s98, 0x8000
	s_addc_u32 s99, s99, 0
	s_add_u32 s100, s100, 0x1000
	s_addc_u32 s101, s101, 0
	s_waitcnt vmcnt(45)
	v_cvt_pk_bf16_f32 v234, v222, v223
	v_cvt_pk_bf16_f32 v235, v224, v225
	v_lshlrev_b32_e32 v226, 16, v186
	v_and_b32_e32 v227, 0xffff0000, v186
	v_lshlrev_b32_e32 v228, 16, v187
	v_and_b32_e32 v229, 0xffff0000, v187
	global_store_dwordx2 v236, v[234:235], s[12:13]
	v_pk_fma_f32 v[222:223], v[222:223], v[4:5], v[226:227]
	v_pk_fma_f32 v[224:225], v[224:225], v[6:7], v[228:229]
	s_add_u32 s12, s12, 0x8000
	s_addc_u32 s13, s13, 0
	global_load_dwordx2 v[186:187], v236, s[98:99]
	global_load_dwordx4 v[4:7], v237, s[100:101]
	s_add_u32 s98, s98, 0x8000
	s_addc_u32 s99, s99, 0
	s_waitcnt vmcnt(45)
	v_cvt_pk_bf16_f32 v238, v222, v223
	v_cvt_pk_bf16_f32 v239, v224, v225
	v_lshlrev_b32_e32 v226, 16, v188
	v_and_b32_e32 v227, 0xffff0000, v188
	v_lshlrev_b32_e32 v228, 16, v189
	v_and_b32_e32 v229, 0xffff0000, v189
	global_store_dwordx2 v236, v[238:239], s[12:13]
	v_pk_fma_f32 v[222:223], v[222:223], v[8:9], v[226:227]
	v_pk_fma_f32 v[224:225], v[224:225], v[10:11], v[228:229]
	s_add_u32 s12, s12, 0x8000
	s_addc_u32 s13, s13, 0
	global_load_dwordx2 v[188:189], v236, s[98:99]
	global_load_dwordx4 v[8:11], v237, s[100:101] offset:512
	s_add_u32 s98, s98, 0x8000
	s_addc_u32 s99, s99, 0
	s_waitcnt vmcnt(45)
	v_cvt_pk_bf16_f32 v234, v222, v223
	v_cvt_pk_bf16_f32 v235, v224, v225
	v_lshlrev_b32_e32 v226, 16, v190
	v_and_b32_e32 v227, 0xffff0000, v190
	v_lshlrev_b32_e32 v228, 16, v191
	v_and_b32_e32 v229, 0xffff0000, v191
	global_store_dwordx2 v236, v[234:235], s[12:13]
	v_pk_fma_f32 v[222:223], v[222:223], v[12:13], v[226:227]
	v_pk_fma_f32 v[224:225], v[224:225], v[14:15], v[228:229]
	s_add_u32 s12, s12, 0x8000
	s_addc_u32 s13, s13, 0
	global_load_dwordx2 v[190:191], v236, s[98:99]
	global_load_dwordx4 v[12:15], v237, s[100:101] offset:1024
	s_add_u32 s98, s98, 0x8000
	s_addc_u32 s99, s99, 0
	s_waitcnt vmcnt(45)
	v_cvt_pk_bf16_f32 v238, v222, v223
	v_cvt_pk_bf16_f32 v239, v224, v225
	v_lshlrev_b32_e32 v226, 16, v192
	v_and_b32_e32 v227, 0xffff0000, v192
	v_lshlrev_b32_e32 v228, 16, v193
	v_and_b32_e32 v229, 0xffff0000, v193
	global_store_dwordx2 v236, v[238:239], s[12:13]
	v_pk_fma_f32 v[222:223], v[222:223], v[16:17], v[226:227]
	v_pk_fma_f32 v[224:225], v[224:225], v[18:19], v[228:229]
	s_add_u32 s12, s12, 0x8000
	s_addc_u32 s13, s13, 0
	global_load_dwordx2 v[192:193], v236, s[98:99]
	global_load_dwordx4 v[16:19], v237, s[100:101] offset:1536
	s_add_u32 s98, s98, 0x8000
	s_addc_u32 s99, s99, 0
	s_waitcnt vmcnt(45)
	v_cvt_pk_bf16_f32 v234, v222, v223
	v_cvt_pk_bf16_f32 v235, v224, v225
	v_lshlrev_b32_e32 v226, 16, v194
	v_and_b32_e32 v227, 0xffff0000, v194
	v_lshlrev_b32_e32 v228, 16, v195
	v_and_b32_e32 v229, 0xffff0000, v195
	global_store_dwordx2 v236, v[234:235], s[12:13]
	v_pk_fma_f32 v[222:223], v[222:223], v[20:21], v[226:227]
	v_pk_fma_f32 v[224:225], v[224:225], v[22:23], v[228:229]
	s_add_u32 s12, s12, 0x8000
	s_addc_u32 s13, s13, 0
	global_load_dwordx2 v[194:195], v236, s[98:99]
	global_load_dwordx4 v[20:23], v237, s[100:101] offset:2048
	s_add_u32 s98, s98, 0x8000
	s_addc_u32 s99, s99, 0
	s_waitcnt vmcnt(45)
	v_cvt_pk_bf16_f32 v238, v222, v223
	v_cvt_pk_bf16_f32 v239, v224, v225
	v_lshlrev_b32_e32 v226, 16, v196
	v_and_b32_e32 v227, 0xffff0000, v196
	v_lshlrev_b32_e32 v228, 16, v197
	v_and_b32_e32 v229, 0xffff0000, v197
	global_store_dwordx2 v236, v[238:239], s[12:13]
	v_pk_fma_f32 v[222:223], v[222:223], v[24:25], v[226:227]
	v_pk_fma_f32 v[224:225], v[224:225], v[26:27], v[228:229]
	s_add_u32 s12, s12, 0x8000
	s_addc_u32 s13, s13, 0
	global_load_dwordx2 v[196:197], v236, s[98:99]
	global_load_dwordx4 v[24:27], v237, s[100:101] offset:2560
	s_add_u32 s98, s98, 0x8000
	s_addc_u32 s99, s99, 0
	s_waitcnt vmcnt(45)
; __device__ __forceinline__ unsigned cvt_pk_bf16(float lo, float hi) { unsigned r; asm volatile("v_cvt_pk_bf16_f32 %0, %1, %2" : "=v"(r) : "v"(lo), "v"(hi)); return r; }
; __device__ __forceinline__ float bflo(unsigned w) { return __uint_as_float(w << 16); }
; __device__ __forceinline__ float bfhi(unsigned w) { return __uint_as_float(w & 0xffff0000u); }
; __device__ void hgrn_scan(const float* ust, const float* ddec, bf16_t* sst, const int WID) {
;     ...
;         for (int c = 0; c < 64; ++c) {
;             const u32x2 uw = *(const u32x2*)(up + (size_t)c * 16384); const f32x4 U = (f32x4){bflo(uw.x), bfhi(uw.x), bflo(uw.y), bfhi(uw.y)}; const f32x4 Dv = *(const f32x4*)(dp + c * 128);
;             u32x2 w; w.x = cvt_pk_bf16(S[0], S[1]); w.y = cvt_pk_bf16(S[2], S[3]); *(u32x2*)(sp + (size_t)c * 16384) = w;
;             S = Dv * S + U;
;         }
	v_cvt_pk_bf16_f32 v234, v222, v223
	v_cvt_pk_bf16_f32 v235, v224, v225
	v_lshlrev_b32_e32 v226, 16, v198
	v_and_b32_e32 v227, 0xffff0000, v198
	v_lshlrev_b32_e32 v228, 16, v199
	v_and_b32_e32 v229, 0xffff0000, v199
	global_store_dwordx2 v236, v[234:235], s[12:13]
	v_pk_fma_f32 v[222:223], v[222:223], v[28:29], v[226:227]
	v_pk_fma_f32 v[224:225], v[224:225], v[30:31], v[228:229]
	s_add_u32 s12, s12, 0x8000
	s_addc_u32 s13, s13, 0
	global_load_dwordx2 v[198:199], v236, s[98:99]
	global_load_dwordx4 v[28:31], v237, s[100:101] offset:3072
	s_add_u32 s98, s98, 0x8000
	s_addc_u32 s99, s99, 0
	s_waitcnt vmcnt(45)
	v_cvt_pk_bf16_f32 v238, v222, v223
	v_cvt_pk_bf16_f32 v239, v224, v225
	v_lshlrev_b32_e32 v226, 16, v200
	v_and_b32_e32 v227, 0xffff0000, v200
	v_lshlrev_b32_e32 v228, 16, v201
	v_and_b32_e32 v229, 0xffff0000, v201
	global_store_dwordx2 v236, v[238:239], s[12:13]
	v_pk_fma_f32 v[222:223], v[222:223], v[32:33], v[226:227]
	v_pk_fma_f32 v[224:225], v[224:225], v[34:35], v[228:229]
	s_add_u32 s12, s12, 0x8000
	s_addc_u32 s13, s13, 0
	global_load_dwordx2 v[200:201], v236, s[98:99]
	global_load_dwordx4 v[32:35], v237, s[100:101] offset:3584
	s_add_u32 s98, s98, 0x8000
	s_addc_u32 s99, s99, 0
	s_add_u32 s100, s100, 0x1000
	s_addc_u32 s101, s101, 0
	s_waitcnt vmcnt(45)
	v_cvt_pk_bf16_f32 v234, v222, v223
	v_cvt_pk_bf16_f32 v235, v224, v225
	v_lshlrev_b32_e32 v226, 16, v202
	v_and_b32_e32 v227, 0xffff0000, v202
	v_lshlrev_b32_e32 v228, 16, v203
	v_and_b32_e32 v229, 0xffff0000, v203
	global_store_dwordx2 v236, v[234:235], s[12:13]
	v_pk_fma_f32 v[222:223], v[222:223], v[116:117], v[226:227]
	v_pk_fma_f32 v[224:225], v[224:225], v[118:119], v[228:229]
	s_add_u32 s12, s12, 0x8000
	s_addc_u32 s13, s13, 0
	global_load_dwordx2 v[202:203], v236, s[98:99]
	global_load_dwordx4 v[116:119], v237, s[100:101]
	s_add_u32 s98, s98, 0x8000
	s_addc_u32 s99, s99, 0
	s_waitcnt vmcnt(45)
	v_cvt_pk_bf16_f32 v238, v222, v223
	v_cvt_pk_bf16_f32 v239, v224, v225
	v_lshlrev_b32_e32 v226, 16, v204
	v_and_b32_e32 v227, 0xffff0000, v204
	v_lshlrev_b32_e32 v228, 16, v205
	v_and_b32_e32 v229, 0xffff0000, v205
	global_store_dwordx2 v236, v[238:239], s[12:13]
	v_pk_fma_f32 v[222:223], v[222:223], v[120:121], v[226:227]
	v_pk_fma_f32 v[224:225], v[224:225], v[122:123], v[228:229]
	s_add_u32 s12, s12, 0x8000
	s_addc_u32 s13, s13, 0
	global_load_dwordx2 v[204:205], v236, s[98:99]
	global_load_dwordx4 v[120:123], v237, s[100:101] offset:512
	s_add_u32 s98, s98, 0x8000
	s_addc_u32 s99, s99, 0
	s_waitcnt vmcnt(45)
	v_cvt_pk_bf16_f32 v234, v222, v223
	v_cvt_pk_bf16_f32 v235, v224, v225
	v_lshlrev_b32_e32 v226, 16, v206
	v_and_b32_e32 v227, 0xffff0000, v206
	v_lshlrev_b32_e32 v228, 16, v207
	v_and_b32_e32 v229, 0xffff0000, v207
	global_store_dwordx2 v236, v[234:235], s[12:13]
	v_pk_fma_f32 v[222:223], v[222:223], v[124:125], v[226:227]
	v_pk_fma_f32 v[224:225], v[224:225], v[126:127], v[228:229]
	s_add_u32 s12, s12, 0x8000
	s_addc_u32 s13, s13, 0
	global_load_dwordx2 v[206:207], v236, s[98:99]
	global_load_dwordx4 v[124:127], v237, s[100:101] offset:1024
	s_add_u32 s98, s98, 0x8000
	s_addc_u32 s99, s99, 0
	s_waitcnt vmcnt(45)
	v_cvt_pk_bf16_f32 v238, v222, v223
	v_cvt_pk_bf16_f32 v239, v224, v225
	v_lshlrev_b32_e32 v226, 16, v214
	v_and_b32_e32 v227, 0xffff0000, v214
	v_lshlrev_b32_e32 v228, 16, v215
	v_and_b32_e32 v229, 0xffff0000, v215
	global_store_dwordx2 v236, v[238:239], s[12:13]
	v_pk_fma_f32 v[222:223], v[222:223], v[128:129], v[226:227]
	v_pk_fma_f32 v[224:225], v[224:225], v[130:131], v[228:229]
	s_add_u32 s12, s12, 0x8000
	s_addc_u32 s13, s13, 0
	global_load_dwordx2 v[214:215], v236, s[98:99]
	global_load_dwordx4 v[128:131], v237, s[100:101] offset:1536
	s_add_u32 s98, s98, 0x8000
	s_addc_u32 s99, s99, 0
	s_waitcnt vmcnt(45)
	v_cvt_pk_bf16_f32 v234, v222, v223
	v_cvt_pk_bf16_f32 v235, v224, v225
	v_lshlrev_b32_e32 v226, 16, v216
	v_and_b32_e32 v227, 0xffff0000, v216
	v_lshlrev_b32_e32 v228, 16, v217
	v_and_b32_e32 v229, 0xffff0000, v217
	global_store_dwordx2 v236, v[234:235], s[12:13]
	v_pk_fma_f32 v[222:223], v[222:223], v[164:165], v[226:227]
	v_pk_fma_f32 v[224:225], v[224:225], v[166:167], v[228:229]
	s_add_u32 s12, s12, 0x8000
	s_addc_u32 s13, s13, 0
	global_load_dwordx2 v[216:217], v236, s[98:99]
	global_load_dwordx4 v[164:167], v237, s[100:101] offset:2048
	s_add_u32 s98, s98, 0x8000
	s_addc_u32 s99, s99, 0
	s_waitcnt vmcnt(45)
	v_cvt_pk_bf16_f32 v238, v222, v223
	v_cvt_pk_bf16_f32 v239, v224, v225
	v_lshlrev_b32_e32 v226, 16, v218
	v_and_b32_e32 v227, 0xffff0000, v218
	v_lshlrev_b32_e32 v228, 16, v219
	v_and_b32_e32 v229, 0xffff0000, v219
	global_store_dwordx2 v236, v[238:239], s[12:13]
	v_pk_fma_f32 v[222:223], v[222:223], v[168:169], v[226:227]
	v_pk_fma_f32 v[224:225], v[224:225], v[170:171], v[228:229]
	s_add_u32 s12, s12, 0x8000
	s_addc_u32 s13, s13, 0
	global_load_dwordx2 v[218:219], v236, s[98:99]
	global_load_dwordx4 v[168:171], v237, s[100:101] offset:2560
	s_add_u32 s98, s98, 0x8000
	s_addc_u32 s99, s99, 0
	s_waitcnt vmcnt(45)
	v_cvt_pk_bf16_f32 v234, v222, v223
	v_cvt_pk_bf16_f32 v235, v224, v225
	v_lshlrev_b32_e32 v226, 16, v220
	v_and_b32_e32 v227, 0xffff0000, v220
	v_lshlrev_b32_e32 v228, 16, v221
	v_and_b32_e32 v229, 0xffff0000, v221
	global_store_dwordx2 v236, v[234:235], s[12:13]
	v_pk_fma_f32 v[222:223], v[222:223], v[172:173], v[226:227]
	v_pk_fma_f32 v[224:225], v[224:225], v[174:175], v[228:229]
	s_add_u32 s12, s12, 0x8000
	s_addc_u32 s13, s13, 0
	global_load_dwordx2 v[220:221], v236, s[98:99]
	global_load_dwordx4 v[172:175], v237, s[100:101] offset:3072
	s_add_u32 s98, s98, 0x8000
	s_addc_u32 s99, s99, 0
	s_waitcnt vmcnt(45)
; __device__ __forceinline__ unsigned cvt_pk_bf16(float lo, float hi) { unsigned r; asm volatile("v_cvt_pk_bf16_f32 %0, %1, %2" : "=v"(r) : "v"(lo), "v"(hi)); return r; }
; __device__ __forceinline__ float bflo(unsigned w) { return __uint_as_float(w << 16); }
; __device__ __forceinline__ float bfhi(unsigned w) { return __uint_as_float(w & 0xffff0000u); }
; __device__ void hgrn_scan(const float* ust, const float* ddec, bf16_t* sst, const int WID) {
;     ...
;         for (int c = 0; c < 64; ++c) {
;             const u32x2 uw = *(const u32x2*)(up + (size_t)c * 16384); const f32x4 U = (f32x4){bflo(uw.x), bfhi(uw.x), bflo(uw.y), bfhi(uw.y)}; const f32x4 Dv = *(const f32x4*)(dp + c * 128);
;             u32x2 w; w.x = cvt_pk_bf16(S[0], S[1]); w.y = cvt_pk_bf16(S[2], S[3]); *(u32x2*)(sp + (size_t)c * 16384) = w;
;             S = Dv * S + U;
;         }
	v_cvt_pk_bf16_f32 v238, v222, v223
	v_cvt_pk_bf16_f32 v239, v224, v225
	v_lshlrev_b32_e32 v226, 16, v44
	v_and_b32_e32 v227, 0xffff0000, v44
	v_lshlrev_b32_e32 v228, 16, v45
	v_and_b32_e32 v229, 0xffff0000, v45
	global_store_dwordx2 v236, v[238:239], s[12:13]
	v_pk_fma_f32 v[222:223], v[222:223], v[176:177], v[226:227]
	v_pk_fma_f32 v[224:225], v[224:225], v[178:179], v[228:229]
	s_add_u32 s12, s12, 0x8000
	s_addc_u32 s13, s13, 0
	global_load_dwordx2 v[44:45], v236, s[98:99]
	global_load_dwordx4 v[176:179], v237, s[100:101] offset:3584
	s_add_u32 s98, s98, 0x8000
	s_addc_u32 s99, s99, 0
	s_add_u32 s100, s100, 0x1000
	s_addc_u32 s101, s101, 0
	s_waitcnt vmcnt(45)
	v_cvt_pk_bf16_f32 v234, v222, v223
	v_cvt_pk_bf16_f32 v235, v224, v225
	v_lshlrev_b32_e32 v226, 16, v186
	v_and_b32_e32 v227, 0xffff0000, v186
	v_lshlrev_b32_e32 v228, 16, v187
	v_and_b32_e32 v229, 0xffff0000, v187
	global_store_dwordx2 v236, v[234:235], s[12:13]
	v_pk_fma_f32 v[222:223], v[222:223], v[4:5], v[226:227]
	v_pk_fma_f32 v[224:225], v[224:225], v[6:7], v[228:229]
	s_add_u32 s12, s12, 0x8000
	s_addc_u32 s13, s13, 0
	global_load_dwordx2 v[186:187], v236, s[98:99]
	global_load_dwordx4 v[4:7], v237, s[100:101]
	s_add_u32 s98, s98, 0x8000
	s_addc_u32 s99, s99, 0
	s_waitcnt vmcnt(45)
	v_cvt_pk_bf16_f32 v238, v222, v223
	v_cvt_pk_bf16_f32 v239, v224, v225
	v_lshlrev_b32_e32 v226, 16, v188
	v_and_b32_e32 v227, 0xffff0000, v188
	v_lshlrev_b32_e32 v228, 16, v189
	v_and_b32_e32 v229, 0xffff0000, v189
	global_store_dwordx2 v236, v[238:239], s[12:13]
	v_pk_fma_f32 v[222:223], v[222:223], v[8:9], v[226:227]
	v_pk_fma_f32 v[224:225], v[224:225], v[10:11], v[228:229]
	s_add_u32 s12, s12, 0x8000
	s_addc_u32 s13, s13, 0
	global_load_dwordx2 v[188:189], v236, s[98:99]
	global_load_dwordx4 v[8:11], v237, s[100:101] offset:512
	s_add_u32 s98, s98, 0x8000
	s_addc_u32 s99, s99, 0
	s_waitcnt vmcnt(45)
	v_cvt_pk_bf16_f32 v234, v222, v223
	v_cvt_pk_bf16_f32 v235, v224, v225
	v_lshlrev_b32_e32 v226, 16, v190
	v_and_b32_e32 v227, 0xffff0000, v190
	v_lshlrev_b32_e32 v228, 16, v191
	v_and_b32_e32 v229, 0xffff0000, v191
	global_store_dwordx2 v236, v[234:235], s[12:13]
	v_pk_fma_f32 v[222:223], v[222:223], v[12:13], v[226:227]
	v_pk_fma_f32 v[224:225], v[224:225], v[14:15], v[228:229]
	s_add_u32 s12, s12, 0x8000
	s_addc_u32 s13, s13, 0
	global_load_dwordx2 v[190:191], v236, s[98:99]
	global_load_dwordx4 v[12:15], v237, s[100:101] offset:1024
	s_add_u32 s98, s98, 0x8000
	s_addc_u32 s99, s99, 0
	s_waitcnt vmcnt(45)
	v_cvt_pk_bf16_f32 v238, v222, v223
	v_cvt_pk_bf16_f32 v239, v224, v225
	v_lshlrev_b32_e32 v226, 16, v192
	v_and_b32_e32 v227, 0xffff0000, v192
	v_lshlrev_b32_e32 v228, 16, v193
	v_and_b32_e32 v229, 0xffff0000, v193
	global_store_dwordx2 v236, v[238:239], s[12:13]
	v_pk_fma_f32 v[222:223], v[222:223], v[16:17], v[226:227]
	v_pk_fma_f32 v[224:225], v[224:225], v[18:19], v[228:229]
	s_add_u32 s12, s12, 0x8000
	s_addc_u32 s13, s13, 0
	global_load_dwordx2 v[192:193], v236, s[98:99]
	global_load_dwordx4 v[16:19], v237, s[100:101] offset:1536
	s_add_u32 s98, s98, 0x8000
	s_addc_u32 s99, s99, 0
	s_waitcnt vmcnt(45)
	v_cvt_pk_bf16_f32 v234, v222, v223
	v_cvt_pk_bf16_f32 v235, v224, v225
	v_lshlrev_b32_e32 v226, 16, v194
	v_and_b32_e32 v227, 0xffff0000, v194
	v_lshlrev_b32_e32 v228, 16, v195
	v_and_b32_e32 v229, 0xffff0000, v195
	global_store_dwordx2 v236, v[234:235], s[12:13]
	v_pk_fma_f32 v[222:223], v[222:223], v[20:21], v[226:227]
	v_pk_fma_f32 v[224:225], v[224:225], v[22:23], v[228:229]
	s_add_u32 s12, s12, 0x8000
	s_addc_u32 s13, s13, 0
	global_load_dwordx2 v[194:195], v236, s[98:99]
	global_load_dwordx4 v[20:23], v237, s[100:101] offset:2048
	s_add_u32 s98, s98, 0x8000
	s_addc_u32 s99, s99, 0
	s_waitcnt vmcnt(45)
	v_cvt_pk_bf16_f32 v238, v222, v223
	v_cvt_pk_bf16_f32 v239, v224, v225
	v_lshlrev_b32_e32 v226, 16, v196
	v_and_b32_e32 v227, 0xffff0000, v196
	v_lshlrev_b32_e32 v228, 16, v197
	v_and_b32_e32 v229, 0xffff0000, v197
	global_store_dwordx2 v236, v[238:239], s[12:13]
	v_pk_fma_f32 v[222:223], v[222:223], v[24:25], v[226:227]
	v_pk_fma_f32 v[224:225], v[224:225], v[26:27], v[228:229]
	s_add_u32 s12, s12, 0x8000
	s_addc_u32 s13, s13, 0
	global_load_dwordx2 v[196:197], v236, s[98:99]
	global_load_dwordx4 v[24:27], v237, s[100:101] offset:2560
	s_add_u32 s98, s98, 0x8000
	s_addc_u32 s99, s99, 0
	s_waitcnt vmcnt(45)
	v_cvt_pk_bf16_f32 v234, v222, v223
	v_cvt_pk_bf16_f32 v235, v224, v225
	v_lshlrev_b32_e32 v226, 16, v198
	v_and_b32_e32 v227, 0xffff0000, v198
	v_lshlrev_b32_e32 v228, 16, v199
	v_and_b32_e32 v229, 0xffff0000, v199
	global_store_dwordx2 v236, v[234:235], s[12:13]
	v_pk_fma_f32 v[222:223], v[222:223], v[28:29], v[226:227]
	v_pk_fma_f32 v[224:225], v[224:225], v[30:31], v[228:229]
	s_add_u32 s12, s12, 0x8000
	s_addc_u32 s13, s13, 0
	global_load_dwordx2 v[198:199], v236, s[98:99]
	global_load_dwordx4 v[28:31], v237, s[100:101] offset:3072
	s_add_u32 s98, s98, 0x8000
	s_addc_u32 s99, s99, 0
	s_waitcnt vmcnt(45)
	v_cvt_pk_bf16_f32 v238, v222, v223
	v_cvt_pk_bf16_f32 v239, v224, v225
	v_lshlrev_b32_e32 v226, 16, v200
	v_and_b32_e32 v227, 0xffff0000, v200
	v_lshlrev_b32_e32 v228, 16, v201
	v_and_b32_e32 v229, 0xffff0000, v201
	global_store_dwordx2 v236, v[238:239], s[12:13]
	v_pk_fma_f32 v[222:223], v[222:223], v[32:33], v[226:227]
	v_pk_fma_f32 v[224:225], v[224:225], v[34:35], v[228:229]
	s_add_u32 s12, s12, 0x8000
	s_addc_u32 s13, s13, 0
	global_load_dwordx2 v[200:201], v236, s[98:99]
	global_load_dwordx4 v[32:35], v237, s[100:101] offset:3584
	s_add_u32 s98, s98, 0x8000
	s_addc_u32 s99, s99, 0
	s_add_u32 s100, s100, 0x1000
	s_addc_u32 s101, s101, 0
	s_waitcnt vmcnt(45)
; __device__ __forceinline__ unsigned cvt_pk_bf16(float lo, float hi) { unsigned r; asm volatile("v_cvt_pk_bf16_f32 %0, %1, %2" : "=v"(r) : "v"(lo), "v"(hi)); return r; }
; __device__ __forceinline__ float bflo(unsigned w) { return __uint_as_float(w << 16); }
; __device__ __forceinline__ float bfhi(unsigned w) { return __uint_as_float(w & 0xffff0000u); }
; __device__ void hgrn_scan(const float* ust, const float* ddec, bf16_t* sst, const int WID) {
;     ...
;         for (int c = 0; c < 64; ++c) {
;             const u32x2 uw = *(const u32x2*)(up + (size_t)c * 16384); const f32x4 U = (f32x4){bflo(uw.x), bfhi(uw.x), bflo(uw.y), bfhi(uw.y)}; const f32x4 Dv = *(const f32x4*)(dp + c * 128);
;             u32x2 w; w.x = cvt_pk_bf16(S[0], S[1]); w.y = cvt_pk_bf16(S[2], S[3]); *(u32x2*)(sp + (size_t)c * 16384) = w;
;             S = Dv * S + U;
;         }
	v_cvt_pk_bf16_f32 v234, v222, v223
	v_cvt_pk_bf16_f32 v235, v224, v225
	v_lshlrev_b32_e32 v226, 16, v202
	v_and_b32_e32 v227, 0xffff0000, v202
	v_lshlrev_b32_e32 v228, 16, v203
	v_and_b32_e32 v229, 0xffff0000, v203
	global_store_dwordx2 v236, v[234:235], s[12:13]
	v_pk_fma_f32 v[222:223], v[222:223], v[116:117], v[226:227]
	v_pk_fma_f32 v[224:225], v[224:225], v[118:119], v[228:229]
	s_add_u32 s12, s12, 0x8000
	s_addc_u32 s13, s13, 0
	global_load_dwordx2 v[202:203], v236, s[98:99]
	global_load_dwordx4 v[116:119], v237, s[100:101]
	s_add_u32 s98, s98, 0x8000
	s_addc_u32 s99, s99, 0
	s_waitcnt vmcnt(45)
	v_cvt_pk_bf16_f32 v238, v222, v223
	v_cvt_pk_bf16_f32 v239, v224, v225
	v_lshlrev_b32_e32 v226, 16, v204
	v_and_b32_e32 v227, 0xffff0000, v204
	v_lshlrev_b32_e32 v228, 16, v205
	v_and_b32_e32 v229, 0xffff0000, v205
	global_store_dwordx2 v236, v[238:239], s[12:13]
	v_pk_fma_f32 v[222:223], v[222:223], v[120:121], v[226:227]
	v_pk_fma_f32 v[224:225], v[224:225], v[122:123], v[228:229]
	s_add_u32 s12, s12, 0x8000
	s_addc_u32 s13, s13, 0
	global_load_dwordx2 v[204:205], v236, s[98:99]
	global_load_dwordx4 v[120:123], v237, s[100:101] offset:512
	s_add_u32 s98, s98, 0x8000
	s_addc_u32 s99, s99, 0
	s_waitcnt vmcnt(45)
	v_cvt_pk_bf16_f32 v234, v222, v223
	v_cvt_pk_bf16_f32 v235, v224, v225
	v_lshlrev_b32_e32 v226, 16, v206
	v_and_b32_e32 v227, 0xffff0000, v206
	v_lshlrev_b32_e32 v228, 16, v207
	v_and_b32_e32 v229, 0xffff0000, v207
	global_store_dwordx2 v236, v[234:235], s[12:13]
	v_pk_fma_f32 v[222:223], v[222:223], v[124:125], v[226:227]
	v_pk_fma_f32 v[224:225], v[224:225], v[126:127], v[228:229]
	s_add_u32 s12, s12, 0x8000
	s_addc_u32 s13, s13, 0
	global_load_dwordx2 v[206:207], v236, s[98:99]
	global_load_dwordx4 v[124:127], v237, s[100:101] offset:1024
	s_add_u32 s98, s98, 0x8000
	s_addc_u32 s99, s99, 0
	s_waitcnt vmcnt(45)
	v_cvt_pk_bf16_f32 v238, v222, v223
	v_cvt_pk_bf16_f32 v239, v224, v225
	v_lshlrev_b32_e32 v226, 16, v214
	v_and_b32_e32 v227, 0xffff0000, v214
	v_lshlrev_b32_e32 v228, 16, v215
	v_and_b32_e32 v229, 0xffff0000, v215
	global_store_dwordx2 v236, v[238:239], s[12:13]
	v_pk_fma_f32 v[222:223], v[222:223], v[128:129], v[226:227]
	v_pk_fma_f32 v[224:225], v[224:225], v[130:131], v[228:229]
	s_add_u32 s12, s12, 0x8000
	s_addc_u32 s13, s13, 0
	global_load_dwordx2 v[214:215], v236, s[98:99]
	global_load_dwordx4 v[128:131], v237, s[100:101] offset:1536
	s_add_u32 s98, s98, 0x8000
	s_addc_u32 s99, s99, 0
	s_waitcnt vmcnt(45)
	v_cvt_pk_bf16_f32 v234, v222, v223
	v_cvt_pk_bf16_f32 v235, v224, v225
	v_lshlrev_b32_e32 v226, 16, v216
	v_and_b32_e32 v227, 0xffff0000, v216
	v_lshlrev_b32_e32 v228, 16, v217
	v_and_b32_e32 v229, 0xffff0000, v217
	global_store_dwordx2 v236, v[234:235], s[12:13]
	v_pk_fma_f32 v[222:223], v[222:223], v[164:165], v[226:227]
	v_pk_fma_f32 v[224:225], v[224:225], v[166:167], v[228:229]
	s_add_u32 s12, s12, 0x8000
	s_addc_u32 s13, s13, 0
	global_load_dwordx2 v[216:217], v236, s[98:99]
	global_load_dwordx4 v[164:167], v237, s[100:101] offset:2048
	s_add_u32 s98, s98, 0x8000
	s_addc_u32 s99, s99, 0
	s_waitcnt vmcnt(45)
	v_cvt_pk_bf16_f32 v238, v222, v223
	v_cvt_pk_bf16_f32 v239, v224, v225
	v_lshlrev_b32_e32 v226, 16, v218
	v_and_b32_e32 v227, 0xffff0000, v218
	v_lshlrev_b32_e32 v228, 16, v219
	v_and_b32_e32 v229, 0xffff0000, v219
	global_store_dwordx2 v236, v[238:239], s[12:13]
	v_pk_fma_f32 v[222:223], v[222:223], v[168:169], v[226:227]
	v_pk_fma_f32 v[224:225], v[224:225], v[170:171], v[228:229]
	s_add_u32 s12, s12, 0x8000
	s_addc_u32 s13, s13, 0
	global_load_dwordx2 v[218:219], v236, s[98:99]
	global_load_dwordx4 v[168:171], v237, s[100:101] offset:2560
	s_add_u32 s98, s98, 0x8000
	s_addc_u32 s99, s99, 0
	s_waitcnt vmcnt(45)
	v_cvt_pk_bf16_f32 v234, v222, v223
	v_cvt_pk_bf16_f32 v235, v224, v225
	v_lshlrev_b32_e32 v226, 16, v220
	v_and_b32_e32 v227, 0xffff0000, v220
	v_lshlrev_b32_e32 v228, 16, v221
	v_and_b32_e32 v229, 0xffff0000, v221
	global_store_dwordx2 v236, v[234:235], s[12:13]
	v_pk_fma_f32 v[222:223], v[222:223], v[172:173], v[226:227]
	v_pk_fma_f32 v[224:225], v[224:225], v[174:175], v[228:229]
	s_add_u32 s12, s12, 0x8000
	s_addc_u32 s13, s13, 0
	global_load_dwordx2 v[220:221], v236, s[98:99]
	global_load_dwordx4 v[172:175], v237, s[100:101] offset:3072
	s_add_u32 s98, s98, 0x8000
	s_addc_u32 s99, s99, 0
	s_waitcnt vmcnt(45)
	v_cvt_pk_bf16_f32 v238, v222, v223
	v_cvt_pk_bf16_f32 v239, v224, v225
	v_lshlrev_b32_e32 v226, 16, v44
	v_and_b32_e32 v227, 0xffff0000, v44
	v_lshlrev_b32_e32 v228, 16, v45
	v_and_b32_e32 v229, 0xffff0000, v45
	global_store_dwordx2 v236, v[238:239], s[12:13]
	v_pk_fma_f32 v[222:223], v[222:223], v[176:177], v[226:227]
	v_pk_fma_f32 v[224:225], v[224:225], v[178:179], v[228:229]
	s_add_u32 s12, s12, 0x8000
	s_addc_u32 s13, s13, 0
	global_load_dwordx2 v[44:45], v236, s[98:99]
	global_load_dwordx4 v[176:179], v237, s[100:101] offset:3584
	s_add_u32 s98, s98, 0x8000
	s_addc_u32 s99, s99, 0
	s_add_u32 s100, s100, 0x1000
	s_addc_u32 s101, s101, 0
	s_waitcnt vmcnt(45)
	v_cvt_pk_bf16_f32 v234, v222, v223
	v_cvt_pk_bf16_f32 v235, v224, v225
	v_lshlrev_b32_e32 v226, 16, v186
	v_and_b32_e32 v227, 0xffff0000, v186
	v_lshlrev_b32_e32 v228, 16, v187
	v_and_b32_e32 v229, 0xffff0000, v187
	global_store_dwordx2 v236, v[234:235], s[12:13]
	v_pk_fma_f32 v[222:223], v[222:223], v[4:5], v[226:227]
	v_pk_fma_f32 v[224:225], v[224:225], v[6:7], v[228:229]
	s_add_u32 s12, s12, 0x8000
	s_addc_u32 s13, s13, 0
	s_waitcnt vmcnt(43)
; __device__ __forceinline__ unsigned cvt_pk_bf16(float lo, float hi) { unsigned r; asm volatile("v_cvt_pk_bf16_f32 %0, %1, %2" : "=v"(r) : "v"(lo), "v"(hi)); return r; }
; __device__ __forceinline__ float bflo(unsigned w) { return __uint_as_float(w << 16); }
; __device__ __forceinline__ float bfhi(unsigned w) { return __uint_as_float(w & 0xffff0000u); }
; __device__ void hgrn_scan(const float* ust, const float* ddec, bf16_t* sst, const int WID) {
;     for (int e4 = blockIdx.x * 512 + TID_X; e4 < 32 * 4096; e4 += gridDim.x * 512) {
;         const int bh = e4 >> 12, off = (e4 & 4095) * 4, d = off & 127;
;         f32x4 S = (f32x4){0.f, 0.f, 0.f, 0.f};
;         const bf16_t* up = (const bf16_t*)ust + (size_t)bh * 64 * 16384 + off; const float* dp = ddec + (size_t)bh * 64 * 128 + d; bf16_t* sp = sst + (size_t)bh * 64 * 16384 + off;
; #pragma unroll 16
;         for (int c = 0; c < 64; ++c) {
;             const u32x2 uw = *(const u32x2*)(up + (size_t)c * 16384); const f32x4 U = (f32x4){bflo(uw.x), bfhi(uw.x), bflo(uw.y), bfhi(uw.y)}; const f32x4 Dv = *(const f32x4*)(dp + c * 128);
;             u32x2 w; w.x = cvt_pk_bf16(S[0], S[1]); w.y = cvt_pk_bf16(S[2], S[3]); *(u32x2*)(sp + (size_t)c * 16384) = w;
;             S = Dv * S + U;
;         }
	v_cvt_pk_bf16_f32 v238, v222, v223
	v_cvt_pk_bf16_f32 v239, v224, v225
	v_lshlrev_b32_e32 v226, 16, v188
	v_and_b32_e32 v227, 0xffff0000, v188
	v_lshlrev_b32_e32 v228, 16, v189
	v_and_b32_e32 v229, 0xffff0000, v189
	global_store_dwordx2 v236, v[238:239], s[12:13]
	v_pk_fma_f32 v[222:223], v[222:223], v[8:9], v[226:227]
	v_pk_fma_f32 v[224:225], v[224:225], v[10:11], v[228:229]
	s_add_u32 s12, s12, 0x8000
	s_addc_u32 s13, s13, 0
	s_waitcnt vmcnt(41)
	v_cvt_pk_bf16_f32 v234, v222, v223
	v_cvt_pk_bf16_f32 v235, v224, v225
	v_lshlrev_b32_e32 v226, 16, v190
	v_and_b32_e32 v227, 0xffff0000, v190
	v_lshlrev_b32_e32 v228, 16, v191
	v_and_b32_e32 v229, 0xffff0000, v191
	global_store_dwordx2 v236, v[234:235], s[12:13]
	v_pk_fma_f32 v[222:223], v[222:223], v[12:13], v[226:227]
	v_pk_fma_f32 v[224:225], v[224:225], v[14:15], v[228:229]
	s_add_u32 s12, s12, 0x8000
	s_addc_u32 s13, s13, 0
	s_waitcnt vmcnt(39)
	v_cvt_pk_bf16_f32 v238, v222, v223
	v_cvt_pk_bf16_f32 v239, v224, v225
	v_lshlrev_b32_e32 v226, 16, v192
	v_and_b32_e32 v227, 0xffff0000, v192
	v_lshlrev_b32_e32 v228, 16, v193
	v_and_b32_e32 v229, 0xffff0000, v193
	global_store_dwordx2 v236, v[238:239], s[12:13]
	v_pk_fma_f32 v[222:223], v[222:223], v[16:17], v[226:227]
	v_pk_fma_f32 v[224:225], v[224:225], v[18:19], v[228:229]
	s_add_u32 s12, s12, 0x8000
	s_addc_u32 s13, s13, 0
	s_waitcnt vmcnt(37)
	v_cvt_pk_bf16_f32 v234, v222, v223
	v_cvt_pk_bf16_f32 v235, v224, v225
	v_lshlrev_b32_e32 v226, 16, v194
	v_and_b32_e32 v227, 0xffff0000, v194
	v_lshlrev_b32_e32 v228, 16, v195
	v_and_b32_e32 v229, 0xffff0000, v195
	global_store_dwordx2 v236, v[234:235], s[12:13]
	v_pk_fma_f32 v[222:223], v[222:223], v[20:21], v[226:227]
	v_pk_fma_f32 v[224:225], v[224:225], v[22:23], v[228:229]
	s_add_u32 s12, s12, 0x8000
	s_addc_u32 s13, s13, 0
	s_waitcnt vmcnt(35)
	v_cvt_pk_bf16_f32 v238, v222, v223
	v_cvt_pk_bf16_f32 v239, v224, v225
	v_lshlrev_b32_e32 v226, 16, v196
	v_and_b32_e32 v227, 0xffff0000, v196
	v_lshlrev_b32_e32 v228, 16, v197
	v_and_b32_e32 v229, 0xffff0000, v197
	global_store_dwordx2 v236, v[238:239], s[12:13]
	v_pk_fma_f32 v[222:223], v[222:223], v[24:25], v[226:227]
	v_pk_fma_f32 v[224:225], v[224:225], v[26:27], v[228:229]
	s_add_u32 s12, s12, 0x8000
	s_addc_u32 s13, s13, 0
	s_waitcnt vmcnt(33)
	v_cvt_pk_bf16_f32 v234, v222, v223
	v_cvt_pk_bf16_f32 v235, v224, v225
	v_lshlrev_b32_e32 v226, 16, v198
	v_and_b32_e32 v227, 0xffff0000, v198
	v_lshlrev_b32_e32 v228, 16, v199
	v_and_b32_e32 v229, 0xffff0000, v199
	global_store_dwordx2 v236, v[234:235], s[12:13]
	v_pk_fma_f32 v[222:223], v[222:223], v[28:29], v[226:227]
	v_pk_fma_f32 v[224:225], v[224:225], v[30:31], v[228:229]
	s_add_u32 s12, s12, 0x8000
	s_addc_u32 s13, s13, 0
	s_waitcnt vmcnt(31)
	v_cvt_pk_bf16_f32 v238, v222, v223
	v_cvt_pk_bf16_f32 v239, v224, v225
	v_lshlrev_b32_e32 v226, 16, v200
	v_and_b32_e32 v227, 0xffff0000, v200
	v_lshlrev_b32_e32 v228, 16, v201
	v_and_b32_e32 v229, 0xffff0000, v201
	global_store_dwordx2 v236, v[238:239], s[12:13]
	v_pk_fma_f32 v[222:223], v[222:223], v[32:33], v[226:227]
	v_pk_fma_f32 v[224:225], v[224:225], v[34:35], v[228:229]
	s_add_u32 s12, s12, 0x8000
	s_addc_u32 s13, s13, 0
	s_waitcnt vmcnt(29)
	v_cvt_pk_bf16_f32 v234, v222, v223
	v_cvt_pk_bf16_f32 v235, v224, v225
	v_lshlrev_b32_e32 v226, 16, v202
	v_and_b32_e32 v227, 0xffff0000, v202
	v_lshlrev_b32_e32 v228, 16, v203
	v_and_b32_e32 v229, 0xffff0000, v203
	global_store_dwordx2 v236, v[234:235], s[12:13]
	v_pk_fma_f32 v[222:223], v[222:223], v[116:117], v[226:227]
	v_pk_fma_f32 v[224:225], v[224:225], v[118:119], v[228:229]
	s_add_u32 s12, s12, 0x8000
	s_addc_u32 s13, s13, 0
	s_waitcnt vmcnt(27)
	v_cvt_pk_bf16_f32 v238, v222, v223
	v_cvt_pk_bf16_f32 v239, v224, v225
	v_lshlrev_b32_e32 v226, 16, v204
	v_and_b32_e32 v227, 0xffff0000, v204
	v_lshlrev_b32_e32 v228, 16, v205
	v_and_b32_e32 v229, 0xffff0000, v205
	global_store_dwordx2 v236, v[238:239], s[12:13]
	v_pk_fma_f32 v[222:223], v[222:223], v[120:121], v[226:227]
	v_pk_fma_f32 v[224:225], v[224:225], v[122:123], v[228:229]
	s_add_u32 s12, s12, 0x8000
	s_addc_u32 s13, s13, 0
	s_waitcnt vmcnt(25)
	v_cvt_pk_bf16_f32 v234, v222, v223
	v_cvt_pk_bf16_f32 v235, v224, v225
	v_lshlrev_b32_e32 v226, 16, v206
	v_and_b32_e32 v227, 0xffff0000, v206
	v_lshlrev_b32_e32 v228, 16, v207
	v_and_b32_e32 v229, 0xffff0000, v207
	global_store_dwordx2 v236, v[234:235], s[12:13]
	v_pk_fma_f32 v[222:223], v[222:223], v[124:125], v[226:227]
	v_pk_fma_f32 v[224:225], v[224:225], v[126:127], v[228:229]
	s_add_u32 s12, s12, 0x8000
	s_addc_u32 s13, s13, 0
	s_waitcnt vmcnt(23)
	v_cvt_pk_bf16_f32 v238, v222, v223
	v_cvt_pk_bf16_f32 v239, v224, v225
	v_lshlrev_b32_e32 v226, 16, v214
	v_and_b32_e32 v227, 0xffff0000, v214
	v_lshlrev_b32_e32 v228, 16, v215
	v_and_b32_e32 v229, 0xffff0000, v215
	global_store_dwordx2 v236, v[238:239], s[12:13]
	v_pk_fma_f32 v[222:223], v[222:223], v[128:129], v[226:227]
	v_pk_fma_f32 v[224:225], v[224:225], v[130:131], v[228:229]
	s_add_u32 s12, s12, 0x8000
	s_addc_u32 s13, s13, 0
	s_waitcnt vmcnt(21)
	v_cvt_pk_bf16_f32 v234, v222, v223
	v_cvt_pk_bf16_f32 v235, v224, v225
	v_lshlrev_b32_e32 v226, 16, v216
	v_and_b32_e32 v227, 0xffff0000, v216
	v_lshlrev_b32_e32 v228, 16, v217
	v_and_b32_e32 v229, 0xffff0000, v217
	global_store_dwordx2 v236, v[234:235], s[12:13]
	v_pk_fma_f32 v[222:223], v[222:223], v[164:165], v[226:227]
	v_pk_fma_f32 v[224:225], v[224:225], v[166:167], v[228:229]
	s_add_u32 s12, s12, 0x8000
	s_addc_u32 s13, s13, 0
	s_waitcnt vmcnt(19)
	v_cvt_pk_bf16_f32 v238, v222, v223
	v_cvt_pk_bf16_f32 v239, v224, v225
	v_lshlrev_b32_e32 v226, 16, v218
	v_and_b32_e32 v227, 0xffff0000, v218
	v_lshlrev_b32_e32 v228, 16, v219
	v_and_b32_e32 v229, 0xffff0000, v219
	global_store_dwordx2 v236, v[238:239], s[12:13]
	v_pk_fma_f32 v[222:223], v[222:223], v[168:169], v[226:227]
	v_pk_fma_f32 v[224:225], v[224:225], v[170:171], v[228:229]
	s_add_u32 s12, s12, 0x8000
	s_addc_u32 s13, s13, 0
	s_waitcnt vmcnt(17)
	v_cvt_pk_bf16_f32 v234, v222, v223
	v_cvt_pk_bf16_f32 v235, v224, v225
	v_lshlrev_b32_e32 v226, 16, v220
	v_and_b32_e32 v227, 0xffff0000, v220
	v_lshlrev_b32_e32 v228, 16, v221
	v_and_b32_e32 v229, 0xffff0000, v221
	global_store_dwordx2 v236, v[234:235], s[12:13]
	v_pk_fma_f32 v[222:223], v[222:223], v[172:173], v[226:227]
	v_pk_fma_f32 v[224:225], v[224:225], v[174:175], v[228:229]
	s_add_u32 s12, s12, 0x8000
	s_addc_u32 s13, s13, 0
	s_waitcnt vmcnt(15)
	v_cvt_pk_bf16_f32 v238, v222, v223
	v_cvt_pk_bf16_f32 v239, v224, v225
	v_lshlrev_b32_e32 v226, 16, v44
	v_and_b32_e32 v227, 0xffff0000, v44
	v_lshlrev_b32_e32 v228, 16, v45
	v_and_b32_e32 v229, 0xffff0000, v45
	global_store_dwordx2 v236, v[238:239], s[12:13]
	v_add_u32_e32 v1, s54, v1
	s_mov_b32 s12, 0x1ffff
	v_cmp_lt_i32_e32 vcc, s12, v1
	s_or_b64 s[10:11], vcc, s[10:11]
	v_add_u32_e32 v18, s24, v18
	s_andn2_b64 exec, exec, s[10:11]
	s_cbranch_execnz .LBB0_216
